# v41 + P1b unit rebalance (state workgroups 6 units, others 9) + reversed P1b tile order + folded-fma gate epilogue
# speedup vs baseline: 1.0392x; 1.0090x over previous
.LBB0_320:
	s_andn2_b64 vcc, exec, s[16:17]
	s_cbranch_vccnz .LBB0_423
	v_ashrrev_i32_e32 v2, 31, v10
	v_lshrrev_b32_e32 v2, 26, v2
	v_add_u32_e32 v2, v10, v2
	v_ashrrev_i32_e32 v11, 6, v2
	v_bfe_i32 v2, v10, 27, 1
	s_waitcnt lgkmcnt(0)
	v_lshlrev_b32_e32 v1, 4, v10
	v_lshrrev_b32_e32 v2, 22, v2
	v_add_u32_e32 v2, v1, v2
	v_and_b32_e32 v2, 0xfffffc00, v2
	v_sub_u32_e32 v2, v1, v2
	v_lshrrev_b32_e32 v3, 4, v2
	s_sub_i32 s1, 14, s1
	s_cmp_lt_i32 s1, 5
	v_bitop3_b32 v2, v3, v2, 32 bitop3:0x6c
	s_cselect_b32 s11, 0, 2
	s_and_b64 s[16:17], s[16:17], exec
	v_ashrrev_i32_e32 v4, 31, v2
	s_cselect_b32 s11, s11, 0
	v_lshrrev_b32_e32 v4, 26, v4
	s_add_i32 s66, s11, s1
	s_ashr_i32 s11, s10, 31
	v_add_u32_e32 v4, v2, v4
	s_lshl_b64 s[16:17], s[10:11], 24
	v_lshlrev_b32_e32 v3, 3, v11
	v_ashrrev_i32_e32 v12, 6, v4
	v_and_b32_e32 v4, 0xc0, v4
	s_add_u32 s1, s30, s16
	v_and_b32_e32 v3, -16, v3
	v_sub_u32_e32 v2, v2, v4
	v_mov_b32_e32 v4, 1
	s_addc_u32 s16, s31, s17
	v_add_u32_e32 v3, v12, v3
	v_ashrrev_i16_sdwa v2, v4, sext(v2) dst_sel:DWORD dst_unused:UNUSED_PAD src0_sel:DWORD src1_sel:BYTE_0
	s_add_u32 s11, s1, 0x1b000000
	v_lshlrev_b32_e32 v5, 5, v11
	v_bfe_i32 v13, v2, 0, 16
	v_lshlrev_b32_e32 v2, 1, v3
	v_lshrrev_b32_e32 v6, 2, v3
	v_and_b32_e32 v7, 3, v12
	s_mov_b32 s1, 0x3fffe0
	v_and_b32_e32 v5, 32, v5
	v_and_b32_e32 v2, 24, v2
	v_and_b32_e32 v6, 4, v6
	v_and_or_b32 v7, v3, s1, v7
	v_or3_b32 v2, v7, v6, v2
	v_add_lshl_u32 v5, v5, v13, 1
	v_add_u32_e32 v1, 0x2000, v1
	v_lshl_add_u32 v156, v2, 10, v5
	v_ashrrev_i32_e32 v2, 31, v1
	v_lshrrev_b32_e32 v2, 22, v2
	v_add_u32_e32 v2, v1, v2
	v_ashrrev_i32_e32 v14, 10, v2
	v_mul_i32_i24_e32 v2, 0x400, v14
	v_sub_u32_e32 v1, v1, v2
	v_lshrrev_b32_e32 v2, 4, v1
	v_bitop3_b32 v1, v2, v1, 32 bitop3:0x6c
	v_lshl_add_u32 v154, v3, 10, v5
	v_ashrrev_i32_e32 v3, 31, v1
	v_lshrrev_b32_e32 v3, 26, v3
	v_add_u32_e32 v3, v1, v3
	v_lshlrev_b32_e32 v2, 3, v14
	v_ashrrev_i32_e32 v15, 6, v3
	v_and_b32_e32 v3, 0xc0, v3
	v_and_b32_e32 v2, -16, v2
	v_sub_u32_e32 v1, v1, v3
	v_add_u32_e32 v2, v15, v2
	v_ashrrev_i16_sdwa v1, v4, sext(v1) dst_sel:DWORD dst_unused:UNUSED_PAD src0_sel:DWORD src1_sel:BYTE_0
	v_and_b32_e32 v4, 3, v15
	s_addc_u32 s83, s16, 0
	s_ashr_i32 s16, s33, 6
	v_and_or_b32 v4, v2, s1, v4
	s_ashr_i32 s1, s0, 31
	s_ashr_i32 s67, s66, 31
	s_ashr_i32 s36, s33, 8
	s_lshl_b32 s84, s16, 10
	s_lshl_b64 s[22:23], s[0:1], 18
	s_lshl_b64 s[24:25], s[66:67], 18
	s_add_u32 s70, s63, s24
	v_lshlrev_b32_e32 v5, 5, v14
	v_bfe_i32 v16, v1, 0, 16
	v_lshlrev_b32_e32 v1, 1, v2
	v_lshrrev_b32_e32 v3, 2, v2
	s_addc_u32 s71, s81, s25
	s_add_i32 s67, s84, 0
	v_and_b32_e32 v5, 32, v5
	v_and_b32_e32 v1, 24, v1
	v_and_b32_e32 v3, 4, v3
	s_add_i32 m0, s67, 0x10000
	v_or3_b32 v1, v4, v3, v1
	v_add_lshl_u32 v3, v5, v16, 1
	global_load_lds_dwordx4 v156, s[70:71]
	s_add_i32 m0, s67, 0x12000
	v_lshl_add_u32 v160, v1, 10, v3
	s_add_u32 s68, s11, s22
	global_load_lds_dwordx4 v160, s[70:71]
	s_addc_u32 s69, s83, s23
	s_mov_b32 m0, s67
	s_add_i32 s85, s67, 0x2000
	v_lshl_add_u32 v158, v2, 10, v3
	global_load_lds_dwordx4 v154, s[68:69]
	s_mov_b32 m0, s85
	s_add_u32 s22, s70, 0x20000
	global_load_lds_dwordx4 v158, s[68:69]
	s_addc_u32 s23, s71, 0
	s_add_i32 m0, s67, 0x14000
	v_writelane_b32 v250, s26, 5
	global_load_lds_dwordx4 v156, s[22:23]
	s_add_i32 m0, s67, 0x16000
	v_writelane_b32 v250, s97, 6
	global_load_lds_dwordx4 v160, s[22:23]
	s_add_u32 s22, s68, 0x20000
	s_addc_u32 s23, s69, 0
	s_add_i32 s86, s67, 0x4000
	v_writelane_b32 v250, s87, 7
	s_mov_b32 m0, s86
	s_add_i32 s87, s67, 0x6000
	global_load_lds_dwordx4 v154, s[22:23]
	s_mov_b32 m0, s87
	v_mov_b32_e32 v167, 0
	global_load_lds_dwordx4 v158, s[22:23]
	v_mov_b32_e32 v157, v167
	v_mov_b32_e32 v161, v167
	v_mov_b32_e32 v155, v167
	v_mov_b32_e32 v159, v167
	s_cmp_eq_u32 s36, 1
	s_mov_b32 s77, s88
	s_mov_b32 s17, 0
	s_movk_i32 s88, 0x2000
	v_lshl_add_u64 v[6:7], s[70:71], 0, v[156:157]
	v_lshl_add_u64 v[4:5], s[70:71], 0, v[160:161]
	v_lshl_add_u64 v[2:3], s[68:69], 0, v[154:155]
	s_cselect_b64 s[22:23], -1, 0
	s_cmp_lg_u32 s36, 1
	v_lshl_add_u64 v[8:9], s[68:69], 0, v[158:159]
	s_cbranch_scc1 .LBB0_323
	s_barrier

.LBB0_326:
	s_mov_b32 s1, s16
	s_add_i32 s16, s16, 1
	s_cmp_gt_u32 s1, 0x3ffffffe
	s_mov_b64 s[52:53], 0
	s_cbranch_scc1 .LBB0_329
	s_lshl_b32 s54, s16, 7
	s_add_u32 s54, s54, s74
	s_mov_b64 s[52:53], 0
	s_cmp_lt_u32 s16, 6
	s_cbranch_scc1 .Lrb_ok
	s_cmp_gt_u32 s74, 63
	s_cbranch_scc1 .LBB0_329
	s_cmp_gt_u32 s16, 8
	s_cbranch_scc1 .LBB0_329
	s_sub_u32 s54, s16, 6
	s_lshl_b32 s54, s54, 6
	s_add_u32 s54, s54, s74
	s_add_u32 s54, s54, 0x300
.Lrb_ok:
	s_ashr_i32 s1, s54, 31
	s_lshr_b32 s1, s1, 29
	s_add_i32 s1, s54, s1
	s_ashr_i32 s33, s1, 3
	s_and_b32 s1, s1, -8
	s_sub_i32 s1, s54, s1
	s_cmp_lt_i32 s1, 0
	s_movk_i32 s46, 0x79
	s_cselect_b32 s46, s46, 0x78
	s_mul_i32 s1, s46, s1
	s_add_i32 s1, s1, s33
	s_mul_hi_i32 s33, s1, 0x88888889
	s_add_i32 s33, s33, s1
	s_lshr_b32 s46, s33, 31
	s_ashr_i32 s33, s33, 5
	s_add_i32 s33, s33, s46
	s_lshl_b32 s46, s33, 2
	s_mul_i32 s33, s33, 60
	s_sub_i32 s1, s1, s33
	s_bfe_i32 s33, s1, 0x80000
	s_bfe_u32 s33, s33, 0x2000d
	s_add_i32 s33, s1, s33
	s_bfe_i32 s47, s33, 0x80000
	s_and_b32 s33, s33, 0xfc
	s_sub_i32 s1, s1, s33
	s_sext_i32_i16 s47, s47
	s_sext_i32_i8 s1, s1
	s_add_i32 s46, s46, s1
	s_ashr_i32 s48, s47, 2
	s_sub_i32 s48, 14, s48
	s_mov_b64 s[52:53], -1

.LBB0_342:
	v_lshl_add_u32 v18, s66, 7, v188
	v_ashrrev_i32_e32 v19, 31, v18
	v_lshlrev_b64 v[2:3], 2, v[18:19]
	v_lshl_add_u64 v[4:5], s[18:19], 0, v[2:3]
	v_lshl_add_u64 v[2:3], s[40:41], 0, v[2:3]
	global_load_dwordx4 v[14:17], v[4:5], off
	global_load_dwordx4 v[10:13], v[2:3], off
	global_load_dwordx4 v[6:9], v[4:5], off offset:16
	s_nop 0
	global_load_dwordx4 v[2:5], v[2:3], off offset:16
	v_add_u32_e32 v22, s47, v163
	v_lshlrev_b64 v[18:19], 1, v[18:19]
	v_ashrrev_i32_e32 v23, 31, v22
	v_lshlrev_b64 v[22:23], 11, v[22:23]
	v_lshl_add_u64 v[22:23], v[22:23], 0, v[18:19]
	v_mov_b32_e32 v236, 0xbd38aa3b
	v_mov_b32_e32 v240, 0x28000
	v_mov_b32_e32 v241, 0
	s_mov_b64 s[0:1], 0x8000
	s_waitcnt vmcnt(0)
	v_mul_f32_e32 v2, 0xbfb8aa3b, v2
	v_mul_f32_e32 v3, 0xbfb8aa3b, v3
	v_mul_f32_e32 v4, 0xbfb8aa3b, v4
	v_mul_f32_e32 v5, 0xbfb8aa3b, v5
	v_mul_f32_e32 v6, 0xbfb8aa3b, v6
	v_mul_f32_e32 v7, 0xbfb8aa3b, v7
	v_mul_f32_e32 v8, 0xbfb8aa3b, v8
	v_mul_f32_e32 v9, 0xbfb8aa3b, v9
	v_mul_f32_e32 v10, 0xbfb8aa3b, v10
	v_mul_f32_e32 v11, 0xbfb8aa3b, v11
	v_mul_f32_e32 v12, 0xbfb8aa3b, v12
	v_mul_f32_e32 v13, 0xbfb8aa3b, v13
	v_mul_f32_e32 v14, 0xbfb8aa3b, v14
	v_mul_f32_e32 v15, 0xbfb8aa3b, v15
	v_mul_f32_e32 v16, 0xbfb8aa3b, v16
	v_mul_f32_e32 v17, 0xbfb8aa3b, v17
	v_lshl_add_u64 v[24:25], s[24:25], 0, v[22:23]
	v_lshl_add_u64 v[238:239], s[26:27], 0, v[22:23]
	v_fma_f32 v150, v150, v236, v14
	v_fma_f32 v151, v151, v236, v15
	v_fma_f32 v152, v152, v236, v16
	v_fma_f32 v153, v153, v236, v17
	v_fma_f32 v146, v146, v236, v6
	v_fma_f32 v147, v147, v236, v7
	v_fma_f32 v148, v148, v236, v8
	v_fma_f32 v149, v149, v236, v9
	v_fma_f32 v142, v142, v236, v10
	v_fma_f32 v143, v143, v236, v11
	v_fma_f32 v144, v144, v236, v12
	v_fma_f32 v145, v145, v236, v13
	v_fma_f32 v138, v138, v236, v2
	v_fma_f32 v139, v139, v236, v3
	v_fma_f32 v140, v140, v236, v4
	v_fma_f32 v141, v141, v236, v5
	v_exp_f32_e32 v150, v150
	v_exp_f32_e32 v151, v151
	v_exp_f32_e32 v152, v152
	v_exp_f32_e32 v153, v153
	v_exp_f32_e32 v146, v146
	v_exp_f32_e32 v147, v147
	v_exp_f32_e32 v148, v148
	v_exp_f32_e32 v149, v149
	v_exp_f32_e32 v142, v142
	v_exp_f32_e32 v143, v143
	v_exp_f32_e32 v144, v144
	v_exp_f32_e32 v145, v145
	v_exp_f32_e32 v138, v138
	v_exp_f32_e32 v139, v139
	v_exp_f32_e32 v140, v140
	v_exp_f32_e32 v141, v141
	v_add_f32_e32 v150, 1.0, v150
	v_add_f32_e32 v151, 1.0, v151
	v_add_f32_e32 v152, 1.0, v152
	v_add_f32_e32 v153, 1.0, v153
	v_add_f32_e32 v146, 1.0, v146
	v_add_f32_e32 v147, 1.0, v147
	v_add_f32_e32 v148, 1.0, v148
	v_add_f32_e32 v149, 1.0, v149
	v_add_f32_e32 v142, 1.0, v142
	v_add_f32_e32 v143, 1.0, v143
	v_add_f32_e32 v144, 1.0, v144
	v_add_f32_e32 v145, 1.0, v145
	v_add_f32_e32 v138, 1.0, v138
	v_add_f32_e32 v139, 1.0, v139
	v_add_f32_e32 v140, 1.0, v140
	v_add_f32_e32 v141, 1.0, v141
	v_rcp_f32_e32 v150, v150
	v_rcp_f32_e32 v151, v151
	v_rcp_f32_e32 v152, v152
	v_rcp_f32_e32 v153, v153
	v_rcp_f32_e32 v146, v146
	v_rcp_f32_e32 v147, v147
	v_rcp_f32_e32 v148, v148
	v_rcp_f32_e32 v149, v149
	v_mul_f32_e32 v150, v142, v150
	v_mul_f32_e32 v151, v143, v151
	v_mul_f32_e32 v152, v144, v152
	v_mul_f32_e32 v153, v145, v153
	v_mul_f32_e32 v146, v138, v146
	v_mul_f32_e32 v147, v139, v147
	v_mul_f32_e32 v148, v140, v148
	v_mul_f32_e32 v149, v141, v149
	v_rcp_f32_e32 v142, v142
	v_rcp_f32_e32 v143, v143
	v_rcp_f32_e32 v144, v144
	v_rcp_f32_e32 v145, v145
	v_rcp_f32_e32 v138, v138
	v_rcp_f32_e32 v139, v139
	v_rcp_f32_e32 v140, v140
	v_rcp_f32_e32 v141, v141
	v_cvt_pk_bf16_f32 v150, v150, v151
	v_cvt_pk_bf16_f32 v151, v152, v153
	v_cvt_pk_bf16_f32 v152, v146, v147
	v_cvt_pk_bf16_f32 v153, v148, v149
	global_store_dwordx4 v[24:25], v[150:153], off nt
	v_cvt_pk_bf16_f32 v142, v142, v143
	v_cvt_pk_bf16_f32 v143, v144, v145
	v_cvt_pk_bf16_f32 v144, v138, v139
	v_cvt_pk_bf16_f32 v145, v140, v141
	global_store_dwordx4 v[238:239], v[142:145], off nt
	v_lshl_add_u64 v[22:23], v[22:23], 0, s[0:1]
	v_lshl_add_u64 v[24:25], s[24:25], 0, v[22:23]
	v_lshl_add_u64 v[238:239], s[26:27], 0, v[22:23]
	v_fma_f32 v134, v134, v236, v14
	v_fma_f32 v135, v135, v236, v15
	v_fma_f32 v136, v136, v236, v16
	v_fma_f32 v137, v137, v236, v17
	v_fma_f32 v130, v130, v236, v6
	v_fma_f32 v131, v131, v236, v7
	v_fma_f32 v132, v132, v236, v8
	v_fma_f32 v133, v133, v236, v9
	v_fma_f32 v126, v126, v236, v10
	v_fma_f32 v127, v127, v236, v11
	v_fma_f32 v128, v128, v236, v12
	v_fma_f32 v129, v129, v236, v13
	v_fma_f32 v122, v122, v236, v2
	v_fma_f32 v123, v123, v236, v3
	v_fma_f32 v124, v124, v236, v4
	v_fma_f32 v125, v125, v236, v5
	v_exp_f32_e32 v134, v134
	v_exp_f32_e32 v135, v135
	v_exp_f32_e32 v136, v136
	v_exp_f32_e32 v137, v137
	v_exp_f32_e32 v130, v130
	v_exp_f32_e32 v131, v131
	v_exp_f32_e32 v132, v132
	v_exp_f32_e32 v133, v133
	v_exp_f32_e32 v126, v126
	v_exp_f32_e32 v127, v127
	v_exp_f32_e32 v128, v128
	v_exp_f32_e32 v129, v129
	v_exp_f32_e32 v122, v122
	v_exp_f32_e32 v123, v123
	v_exp_f32_e32 v124, v124
	v_exp_f32_e32 v125, v125
	v_add_f32_e32 v134, 1.0, v134
	v_add_f32_e32 v135, 1.0, v135
	v_add_f32_e32 v136, 1.0, v136
	v_add_f32_e32 v137, 1.0, v137
	v_add_f32_e32 v130, 1.0, v130
	v_add_f32_e32 v131, 1.0, v131
	v_add_f32_e32 v132, 1.0, v132
	v_add_f32_e32 v133, 1.0, v133
	v_add_f32_e32 v126, 1.0, v126
	v_add_f32_e32 v127, 1.0, v127
	v_add_f32_e32 v128, 1.0, v128
	v_add_f32_e32 v129, 1.0, v129
	v_add_f32_e32 v122, 1.0, v122
	v_add_f32_e32 v123, 1.0, v123
	v_add_f32_e32 v124, 1.0, v124
	v_add_f32_e32 v125, 1.0, v125
	v_rcp_f32_e32 v134, v134
	v_rcp_f32_e32 v135, v135
	v_rcp_f32_e32 v136, v136
	v_rcp_f32_e32 v137, v137
	v_rcp_f32_e32 v130, v130
	v_rcp_f32_e32 v131, v131
	v_rcp_f32_e32 v132, v132
	v_rcp_f32_e32 v133, v133
	v_mul_f32_e32 v134, v126, v134
	v_mul_f32_e32 v135, v127, v135
	v_mul_f32_e32 v136, v128, v136
	v_mul_f32_e32 v137, v129, v137
	v_mul_f32_e32 v130, v122, v130
	v_mul_f32_e32 v131, v123, v131
	v_mul_f32_e32 v132, v124, v132
	v_mul_f32_e32 v133, v125, v133
	v_rcp_f32_e32 v126, v126
	v_rcp_f32_e32 v127, v127
	v_rcp_f32_e32 v128, v128
	v_rcp_f32_e32 v129, v129
	v_rcp_f32_e32 v122, v122
	v_rcp_f32_e32 v123, v123
	v_rcp_f32_e32 v124, v124
	v_rcp_f32_e32 v125, v125
	v_cvt_pk_bf16_f32 v134, v134, v135
	v_cvt_pk_bf16_f32 v135, v136, v137
	v_cvt_pk_bf16_f32 v136, v130, v131
	v_cvt_pk_bf16_f32 v137, v132, v133
	global_store_dwordx4 v[24:25], v[134:137], off nt
	v_cvt_pk_bf16_f32 v126, v126, v127
	v_cvt_pk_bf16_f32 v127, v128, v129
	v_cvt_pk_bf16_f32 v128, v122, v123
	v_cvt_pk_bf16_f32 v129, v124, v125
	global_store_dwordx4 v[238:239], v[126:129], off nt
	v_lshl_add_u64 v[22:23], v[22:23], 0, s[0:1]
	v_lshl_add_u64 v[24:25], s[24:25], 0, v[22:23]
	v_lshl_add_u64 v[238:239], s[26:27], 0, v[22:23]
	v_fma_f32 v118, v118, v236, v14
	v_fma_f32 v119, v119, v236, v15
	v_fma_f32 v120, v120, v236, v16
	v_fma_f32 v121, v121, v236, v17
	v_fma_f32 v114, v114, v236, v6
	v_fma_f32 v115, v115, v236, v7
	v_fma_f32 v116, v116, v236, v8
	v_fma_f32 v117, v117, v236, v9
	v_fma_f32 v110, v110, v236, v10
	v_fma_f32 v111, v111, v236, v11
	v_fma_f32 v112, v112, v236, v12
	v_fma_f32 v113, v113, v236, v13
	v_fma_f32 v106, v106, v236, v2
	v_fma_f32 v107, v107, v236, v3
	v_fma_f32 v108, v108, v236, v4
	v_fma_f32 v109, v109, v236, v5
	v_exp_f32_e32 v118, v118
	v_exp_f32_e32 v119, v119
	v_exp_f32_e32 v120, v120
	v_exp_f32_e32 v121, v121
	v_exp_f32_e32 v114, v114
	v_exp_f32_e32 v115, v115
	v_exp_f32_e32 v116, v116
	v_exp_f32_e32 v117, v117
	v_exp_f32_e32 v110, v110
	v_exp_f32_e32 v111, v111
	v_exp_f32_e32 v112, v112
	v_exp_f32_e32 v113, v113
	v_exp_f32_e32 v106, v106
	v_exp_f32_e32 v107, v107
	v_exp_f32_e32 v108, v108
	v_exp_f32_e32 v109, v109
	v_add_f32_e32 v118, 1.0, v118
	v_add_f32_e32 v119, 1.0, v119
	v_add_f32_e32 v120, 1.0, v120
	v_add_f32_e32 v121, 1.0, v121
	v_add_f32_e32 v114, 1.0, v114
	v_add_f32_e32 v115, 1.0, v115
	v_add_f32_e32 v116, 1.0, v116
	v_add_f32_e32 v117, 1.0, v117
	v_add_f32_e32 v110, 1.0, v110
	v_add_f32_e32 v111, 1.0, v111
	v_add_f32_e32 v112, 1.0, v112
	v_add_f32_e32 v113, 1.0, v113
	v_add_f32_e32 v106, 1.0, v106
	v_add_f32_e32 v107, 1.0, v107
	v_add_f32_e32 v108, 1.0, v108
	v_add_f32_e32 v109, 1.0, v109
	v_rcp_f32_e32 v118, v118
	v_rcp_f32_e32 v119, v119
	v_rcp_f32_e32 v120, v120
	v_rcp_f32_e32 v121, v121
	v_rcp_f32_e32 v114, v114
	v_rcp_f32_e32 v115, v115
	v_rcp_f32_e32 v116, v116
	v_rcp_f32_e32 v117, v117
	v_mul_f32_e32 v118, v110, v118
	v_mul_f32_e32 v119, v111, v119
	v_mul_f32_e32 v120, v112, v120
	v_mul_f32_e32 v121, v113, v121
	v_mul_f32_e32 v114, v106, v114
	v_mul_f32_e32 v115, v107, v115
	v_mul_f32_e32 v116, v108, v116
	v_mul_f32_e32 v117, v109, v117
	v_rcp_f32_e32 v110, v110
	v_rcp_f32_e32 v111, v111
	v_rcp_f32_e32 v112, v112
	v_rcp_f32_e32 v113, v113
	v_rcp_f32_e32 v106, v106
	v_rcp_f32_e32 v107, v107
	v_rcp_f32_e32 v108, v108
	v_rcp_f32_e32 v109, v109
	v_cvt_pk_bf16_f32 v118, v118, v119
	v_cvt_pk_bf16_f32 v119, v120, v121
	v_cvt_pk_bf16_f32 v120, v114, v115
	v_cvt_pk_bf16_f32 v121, v116, v117
	global_store_dwordx4 v[24:25], v[118:121], off nt
	v_cvt_pk_bf16_f32 v110, v110, v111
	v_cvt_pk_bf16_f32 v111, v112, v113
	v_cvt_pk_bf16_f32 v112, v106, v107
	v_cvt_pk_bf16_f32 v113, v108, v109
	global_store_dwordx4 v[238:239], v[110:113], off nt
	v_lshl_add_u64 v[22:23], v[22:23], 0, s[0:1]
	v_lshl_add_u64 v[24:25], s[24:25], 0, v[22:23]
	v_lshl_add_u64 v[238:239], s[26:27], 0, v[22:23]
	v_fma_f32 v102, v102, v236, v14
	v_fma_f32 v103, v103, v236, v15
	v_fma_f32 v104, v104, v236, v16
	v_fma_f32 v105, v105, v236, v17
	v_fma_f32 v98, v98, v236, v6
	v_fma_f32 v99, v99, v236, v7
	v_fma_f32 v100, v100, v236, v8
	v_fma_f32 v101, v101, v236, v9
	v_fma_f32 v94, v94, v236, v10
	v_fma_f32 v95, v95, v236, v11
	v_fma_f32 v96, v96, v236, v12
	v_fma_f32 v97, v97, v236, v13
	v_fma_f32 v90, v90, v236, v2
	v_fma_f32 v91, v91, v236, v3
	v_fma_f32 v92, v92, v236, v4
	v_fma_f32 v93, v93, v236, v5
	v_exp_f32_e32 v102, v102
	v_exp_f32_e32 v103, v103
	v_exp_f32_e32 v104, v104
	v_exp_f32_e32 v105, v105
	v_exp_f32_e32 v98, v98
	v_exp_f32_e32 v99, v99
	v_exp_f32_e32 v100, v100
	v_exp_f32_e32 v101, v101
	v_exp_f32_e32 v94, v94
	v_exp_f32_e32 v95, v95
	v_exp_f32_e32 v96, v96
	v_exp_f32_e32 v97, v97
	v_exp_f32_e32 v90, v90
	v_exp_f32_e32 v91, v91
	v_exp_f32_e32 v92, v92
	v_exp_f32_e32 v93, v93
	v_add_f32_e32 v102, 1.0, v102
	v_add_f32_e32 v103, 1.0, v103
	v_add_f32_e32 v104, 1.0, v104
	v_add_f32_e32 v105, 1.0, v105
	v_add_f32_e32 v98, 1.0, v98
	v_add_f32_e32 v99, 1.0, v99
	v_add_f32_e32 v100, 1.0, v100
	v_add_f32_e32 v101, 1.0, v101
	v_add_f32_e32 v94, 1.0, v94
	v_add_f32_e32 v95, 1.0, v95
	v_add_f32_e32 v96, 1.0, v96
	v_add_f32_e32 v97, 1.0, v97
	v_add_f32_e32 v90, 1.0, v90
	v_add_f32_e32 v91, 1.0, v91
	v_add_f32_e32 v92, 1.0, v92
	v_add_f32_e32 v93, 1.0, v93
	v_rcp_f32_e32 v102, v102
	v_rcp_f32_e32 v103, v103
	v_rcp_f32_e32 v104, v104
	v_rcp_f32_e32 v105, v105
	v_rcp_f32_e32 v98, v98
	v_rcp_f32_e32 v99, v99
	v_rcp_f32_e32 v100, v100
	v_rcp_f32_e32 v101, v101
	v_mul_f32_e32 v102, v94, v102
	v_mul_f32_e32 v103, v95, v103
	v_mul_f32_e32 v104, v96, v104
	v_mul_f32_e32 v105, v97, v105
	v_mul_f32_e32 v98, v90, v98
	v_mul_f32_e32 v99, v91, v99
	v_mul_f32_e32 v100, v92, v100
	v_mul_f32_e32 v101, v93, v101
	v_rcp_f32_e32 v94, v94
	v_rcp_f32_e32 v95, v95
	v_rcp_f32_e32 v96, v96
	v_rcp_f32_e32 v97, v97
	v_rcp_f32_e32 v90, v90
	v_rcp_f32_e32 v91, v91
	v_rcp_f32_e32 v92, v92
	v_rcp_f32_e32 v93, v93
	v_cvt_pk_bf16_f32 v102, v102, v103
	v_cvt_pk_bf16_f32 v103, v104, v105
	v_cvt_pk_bf16_f32 v104, v98, v99
	v_cvt_pk_bf16_f32 v105, v100, v101
	global_store_dwordx4 v[24:25], v[102:105], off nt
	v_cvt_pk_bf16_f32 v94, v94, v95
	v_cvt_pk_bf16_f32 v95, v96, v97
	v_cvt_pk_bf16_f32 v96, v90, v91
	v_cvt_pk_bf16_f32 v97, v92, v93
	global_store_dwordx4 v[238:239], v[94:97], off nt
	v_lshl_add_u64 v[22:23], v[22:23], 0, v[240:241]
	v_lshl_add_u64 v[24:25], s[24:25], 0, v[22:23]
	v_lshl_add_u64 v[238:239], s[26:27], 0, v[22:23]
	v_fma_f32 v86, v86, v236, v14
	v_fma_f32 v87, v87, v236, v15
	v_fma_f32 v88, v88, v236, v16
	v_fma_f32 v89, v89, v236, v17
	v_fma_f32 v82, v82, v236, v6
	v_fma_f32 v83, v83, v236, v7
	v_fma_f32 v84, v84, v236, v8
	v_fma_f32 v85, v85, v236, v9
	v_fma_f32 v78, v78, v236, v10
	v_fma_f32 v79, v79, v236, v11
	v_fma_f32 v80, v80, v236, v12
	v_fma_f32 v81, v81, v236, v13
	v_fma_f32 v74, v74, v236, v2
	v_fma_f32 v75, v75, v236, v3
	v_fma_f32 v76, v76, v236, v4
	v_fma_f32 v77, v77, v236, v5
	v_exp_f32_e32 v86, v86
	v_exp_f32_e32 v87, v87
	v_exp_f32_e32 v88, v88
	v_exp_f32_e32 v89, v89
	v_exp_f32_e32 v82, v82
	v_exp_f32_e32 v83, v83
	v_exp_f32_e32 v84, v84
	v_exp_f32_e32 v85, v85
	v_exp_f32_e32 v78, v78
	v_exp_f32_e32 v79, v79
	v_exp_f32_e32 v80, v80
	v_exp_f32_e32 v81, v81
	v_exp_f32_e32 v74, v74
	v_exp_f32_e32 v75, v75
	v_exp_f32_e32 v76, v76
	v_exp_f32_e32 v77, v77
	v_add_f32_e32 v86, 1.0, v86
	v_add_f32_e32 v87, 1.0, v87
	v_add_f32_e32 v88, 1.0, v88
	v_add_f32_e32 v89, 1.0, v89
	v_add_f32_e32 v82, 1.0, v82
	v_add_f32_e32 v83, 1.0, v83
	v_add_f32_e32 v84, 1.0, v84
	v_add_f32_e32 v85, 1.0, v85
	v_add_f32_e32 v78, 1.0, v78
	v_add_f32_e32 v79, 1.0, v79
	v_add_f32_e32 v80, 1.0, v80
	v_add_f32_e32 v81, 1.0, v81
	v_add_f32_e32 v74, 1.0, v74
	v_add_f32_e32 v75, 1.0, v75
	v_add_f32_e32 v76, 1.0, v76
	v_add_f32_e32 v77, 1.0, v77
	v_rcp_f32_e32 v86, v86
	v_rcp_f32_e32 v87, v87
	v_rcp_f32_e32 v88, v88
	v_rcp_f32_e32 v89, v89
	v_rcp_f32_e32 v82, v82
	v_rcp_f32_e32 v83, v83
	v_rcp_f32_e32 v84, v84
	v_rcp_f32_e32 v85, v85
	v_mul_f32_e32 v86, v78, v86
	v_mul_f32_e32 v87, v79, v87
	v_mul_f32_e32 v88, v80, v88
	v_mul_f32_e32 v89, v81, v89
	v_mul_f32_e32 v82, v74, v82
	v_mul_f32_e32 v83, v75, v83
	v_mul_f32_e32 v84, v76, v84
	v_mul_f32_e32 v85, v77, v85
	v_rcp_f32_e32 v78, v78
	v_rcp_f32_e32 v79, v79
	v_rcp_f32_e32 v80, v80
	v_rcp_f32_e32 v81, v81
	v_rcp_f32_e32 v74, v74
	v_rcp_f32_e32 v75, v75
	v_rcp_f32_e32 v76, v76
	v_rcp_f32_e32 v77, v77
	v_cvt_pk_bf16_f32 v86, v86, v87
	v_cvt_pk_bf16_f32 v87, v88, v89
	v_cvt_pk_bf16_f32 v88, v82, v83
	v_cvt_pk_bf16_f32 v89, v84, v85
	global_store_dwordx4 v[24:25], v[86:89], off nt
	v_cvt_pk_bf16_f32 v78, v78, v79
	v_cvt_pk_bf16_f32 v79, v80, v81
	v_cvt_pk_bf16_f32 v80, v74, v75
	v_cvt_pk_bf16_f32 v81, v76, v77
	global_store_dwordx4 v[238:239], v[78:81], off nt
	v_lshl_add_u64 v[22:23], v[22:23], 0, s[0:1]
	v_lshl_add_u64 v[24:25], s[24:25], 0, v[22:23]
	v_lshl_add_u64 v[238:239], s[26:27], 0, v[22:23]
	v_fma_f32 v70, v70, v236, v14
	v_fma_f32 v71, v71, v236, v15
	v_fma_f32 v72, v72, v236, v16
	v_fma_f32 v73, v73, v236, v17
	v_fma_f32 v66, v66, v236, v6
	v_fma_f32 v67, v67, v236, v7
	v_fma_f32 v68, v68, v236, v8
	v_fma_f32 v69, v69, v236, v9
	v_fma_f32 v62, v62, v236, v10
	v_fma_f32 v63, v63, v236, v11
	v_fma_f32 v64, v64, v236, v12
	v_fma_f32 v65, v65, v236, v13
	v_fma_f32 v58, v58, v236, v2
	v_fma_f32 v59, v59, v236, v3
	v_fma_f32 v60, v60, v236, v4
	v_fma_f32 v61, v61, v236, v5
	v_exp_f32_e32 v70, v70
	v_exp_f32_e32 v71, v71
	v_exp_f32_e32 v72, v72
	v_exp_f32_e32 v73, v73
	v_exp_f32_e32 v66, v66
	v_exp_f32_e32 v67, v67
	v_exp_f32_e32 v68, v68
	v_exp_f32_e32 v69, v69
	v_exp_f32_e32 v62, v62
	v_exp_f32_e32 v63, v63
	v_exp_f32_e32 v64, v64
	v_exp_f32_e32 v65, v65
	v_exp_f32_e32 v58, v58
	v_exp_f32_e32 v59, v59
	v_exp_f32_e32 v60, v60
	v_exp_f32_e32 v61, v61
	v_add_f32_e32 v70, 1.0, v70
	v_add_f32_e32 v71, 1.0, v71
	v_add_f32_e32 v72, 1.0, v72
	v_add_f32_e32 v73, 1.0, v73
	v_add_f32_e32 v66, 1.0, v66
	v_add_f32_e32 v67, 1.0, v67
	v_add_f32_e32 v68, 1.0, v68
	v_add_f32_e32 v69, 1.0, v69
	v_add_f32_e32 v62, 1.0, v62
	v_add_f32_e32 v63, 1.0, v63
	v_add_f32_e32 v64, 1.0, v64
	v_add_f32_e32 v65, 1.0, v65
	v_add_f32_e32 v58, 1.0, v58
	v_add_f32_e32 v59, 1.0, v59
	v_add_f32_e32 v60, 1.0, v60
	v_add_f32_e32 v61, 1.0, v61
	v_rcp_f32_e32 v70, v70
	v_rcp_f32_e32 v71, v71
	v_rcp_f32_e32 v72, v72
	v_rcp_f32_e32 v73, v73
	v_rcp_f32_e32 v66, v66
	v_rcp_f32_e32 v67, v67
	v_rcp_f32_e32 v68, v68
	v_rcp_f32_e32 v69, v69
	v_mul_f32_e32 v70, v62, v70
	v_mul_f32_e32 v71, v63, v71
	v_mul_f32_e32 v72, v64, v72
	v_mul_f32_e32 v73, v65, v73
	v_mul_f32_e32 v66, v58, v66
	v_mul_f32_e32 v67, v59, v67
	v_mul_f32_e32 v68, v60, v68
	v_mul_f32_e32 v69, v61, v69
	v_rcp_f32_e32 v62, v62
	v_rcp_f32_e32 v63, v63
	v_rcp_f32_e32 v64, v64
	v_rcp_f32_e32 v65, v65
	v_rcp_f32_e32 v58, v58
	v_rcp_f32_e32 v59, v59
	v_rcp_f32_e32 v60, v60
	v_rcp_f32_e32 v61, v61
	v_cvt_pk_bf16_f32 v70, v70, v71
	v_cvt_pk_bf16_f32 v71, v72, v73
	v_cvt_pk_bf16_f32 v72, v66, v67
	v_cvt_pk_bf16_f32 v73, v68, v69
	global_store_dwordx4 v[24:25], v[70:73], off nt
	v_cvt_pk_bf16_f32 v62, v62, v63
	v_cvt_pk_bf16_f32 v63, v64, v65
	v_cvt_pk_bf16_f32 v64, v58, v59
	v_cvt_pk_bf16_f32 v65, v60, v61
	global_store_dwordx4 v[238:239], v[62:65], off nt
	v_lshl_add_u64 v[22:23], v[22:23], 0, s[0:1]
	v_lshl_add_u64 v[24:25], s[24:25], 0, v[22:23]
	v_lshl_add_u64 v[238:239], s[26:27], 0, v[22:23]
	v_fma_f32 v54, v54, v236, v14
	v_fma_f32 v55, v55, v236, v15
	v_fma_f32 v56, v56, v236, v16
	v_fma_f32 v57, v57, v236, v17
	v_fma_f32 v50, v50, v236, v6
	v_fma_f32 v51, v51, v236, v7
	v_fma_f32 v52, v52, v236, v8
	v_fma_f32 v53, v53, v236, v9
	v_fma_f32 v46, v46, v236, v10
	v_fma_f32 v47, v47, v236, v11
	v_fma_f32 v48, v48, v236, v12
	v_fma_f32 v49, v49, v236, v13
	v_fma_f32 v42, v42, v236, v2
	v_fma_f32 v43, v43, v236, v3
	v_fma_f32 v44, v44, v236, v4
	v_fma_f32 v45, v45, v236, v5
	v_exp_f32_e32 v54, v54
	v_exp_f32_e32 v55, v55
	v_exp_f32_e32 v56, v56
	v_exp_f32_e32 v57, v57
	v_exp_f32_e32 v50, v50
	v_exp_f32_e32 v51, v51
	v_exp_f32_e32 v52, v52
	v_exp_f32_e32 v53, v53
	v_exp_f32_e32 v46, v46
	v_exp_f32_e32 v47, v47
	v_exp_f32_e32 v48, v48
	v_exp_f32_e32 v49, v49
	v_exp_f32_e32 v42, v42
	v_exp_f32_e32 v43, v43
	v_exp_f32_e32 v44, v44
	v_exp_f32_e32 v45, v45
	v_add_f32_e32 v54, 1.0, v54
	v_add_f32_e32 v55, 1.0, v55
	v_add_f32_e32 v56, 1.0, v56
	v_add_f32_e32 v57, 1.0, v57
	v_add_f32_e32 v50, 1.0, v50
	v_add_f32_e32 v51, 1.0, v51
	v_add_f32_e32 v52, 1.0, v52
	v_add_f32_e32 v53, 1.0, v53
	v_add_f32_e32 v46, 1.0, v46
	v_add_f32_e32 v47, 1.0, v47
	v_add_f32_e32 v48, 1.0, v48
	v_add_f32_e32 v49, 1.0, v49
	v_add_f32_e32 v42, 1.0, v42
	v_add_f32_e32 v43, 1.0, v43
	v_add_f32_e32 v44, 1.0, v44
	v_add_f32_e32 v45, 1.0, v45
	v_rcp_f32_e32 v54, v54
	v_rcp_f32_e32 v55, v55
	v_rcp_f32_e32 v56, v56
	v_rcp_f32_e32 v57, v57
	v_rcp_f32_e32 v50, v50
	v_rcp_f32_e32 v51, v51
	v_rcp_f32_e32 v52, v52
	v_rcp_f32_e32 v53, v53
	v_mul_f32_e32 v54, v46, v54
	v_mul_f32_e32 v55, v47, v55
	v_mul_f32_e32 v56, v48, v56
	v_mul_f32_e32 v57, v49, v57
	v_mul_f32_e32 v50, v42, v50
	v_mul_f32_e32 v51, v43, v51
	v_mul_f32_e32 v52, v44, v52
	v_mul_f32_e32 v53, v45, v53
	v_rcp_f32_e32 v46, v46
	v_rcp_f32_e32 v47, v47
	v_rcp_f32_e32 v48, v48
	v_rcp_f32_e32 v49, v49
	v_rcp_f32_e32 v42, v42
	v_rcp_f32_e32 v43, v43
	v_rcp_f32_e32 v44, v44
	v_rcp_f32_e32 v45, v45
	v_cvt_pk_bf16_f32 v54, v54, v55
	v_cvt_pk_bf16_f32 v55, v56, v57
	v_cvt_pk_bf16_f32 v56, v50, v51
	v_cvt_pk_bf16_f32 v57, v52, v53
	global_store_dwordx4 v[24:25], v[54:57], off nt
	v_cvt_pk_bf16_f32 v46, v46, v47
	v_cvt_pk_bf16_f32 v47, v48, v49
	v_cvt_pk_bf16_f32 v48, v42, v43
	v_cvt_pk_bf16_f32 v49, v44, v45
	global_store_dwordx4 v[238:239], v[46:49], off nt
	v_lshl_add_u64 v[22:23], v[22:23], 0, s[0:1]
	v_lshl_add_u64 v[24:25], s[24:25], 0, v[22:23]
	v_lshl_add_u64 v[238:239], s[26:27], 0, v[22:23]
	v_fma_f32 v38, v38, v236, v14
	v_fma_f32 v39, v39, v236, v15
	v_fma_f32 v40, v40, v236, v16
	v_fma_f32 v41, v41, v236, v17
	v_fma_f32 v34, v34, v236, v6
	v_fma_f32 v35, v35, v236, v7
	v_fma_f32 v36, v36, v236, v8
	v_fma_f32 v37, v37, v236, v9
	v_fma_f32 v30, v30, v236, v10
	v_fma_f32 v31, v31, v236, v11
	v_fma_f32 v32, v32, v236, v12
	v_fma_f32 v33, v33, v236, v13
	v_fma_f32 v26, v26, v236, v2
	v_fma_f32 v27, v27, v236, v3
	v_fma_f32 v28, v28, v236, v4
	v_fma_f32 v29, v29, v236, v5
	v_exp_f32_e32 v38, v38
	v_exp_f32_e32 v39, v39
	v_exp_f32_e32 v40, v40
	v_exp_f32_e32 v41, v41
	v_exp_f32_e32 v34, v34
	v_exp_f32_e32 v35, v35
	v_exp_f32_e32 v36, v36
	v_exp_f32_e32 v37, v37
	v_exp_f32_e32 v30, v30
	v_exp_f32_e32 v31, v31
	v_exp_f32_e32 v32, v32
	v_exp_f32_e32 v33, v33
	v_exp_f32_e32 v26, v26
	v_exp_f32_e32 v27, v27
	v_exp_f32_e32 v28, v28
	v_exp_f32_e32 v29, v29
	v_add_f32_e32 v38, 1.0, v38
	v_add_f32_e32 v39, 1.0, v39
	v_add_f32_e32 v40, 1.0, v40
	v_add_f32_e32 v41, 1.0, v41
	v_add_f32_e32 v34, 1.0, v34
	v_add_f32_e32 v35, 1.0, v35
	v_add_f32_e32 v36, 1.0, v36
	v_add_f32_e32 v37, 1.0, v37
	v_add_f32_e32 v30, 1.0, v30
	v_add_f32_e32 v31, 1.0, v31
	v_add_f32_e32 v32, 1.0, v32
	v_add_f32_e32 v33, 1.0, v33
	v_add_f32_e32 v26, 1.0, v26
	v_add_f32_e32 v27, 1.0, v27
	v_add_f32_e32 v28, 1.0, v28
	v_add_f32_e32 v29, 1.0, v29
	v_rcp_f32_e32 v38, v38
	v_rcp_f32_e32 v39, v39
	v_rcp_f32_e32 v40, v40
	v_rcp_f32_e32 v41, v41
	v_rcp_f32_e32 v34, v34
	v_rcp_f32_e32 v35, v35
	v_rcp_f32_e32 v36, v36
	v_rcp_f32_e32 v37, v37
	v_mul_f32_e32 v38, v30, v38
	v_mul_f32_e32 v39, v31, v39
	v_mul_f32_e32 v40, v32, v40
	v_mul_f32_e32 v41, v33, v41
	v_mul_f32_e32 v34, v26, v34
	v_mul_f32_e32 v35, v27, v35
	v_mul_f32_e32 v36, v28, v36
	v_mul_f32_e32 v37, v29, v37
	v_rcp_f32_e32 v30, v30
	v_rcp_f32_e32 v31, v31
	v_rcp_f32_e32 v32, v32
	v_rcp_f32_e32 v33, v33
	v_rcp_f32_e32 v26, v26
	v_rcp_f32_e32 v27, v27
	v_rcp_f32_e32 v28, v28
	v_rcp_f32_e32 v29, v29
	v_cvt_pk_bf16_f32 v38, v38, v39
	v_cvt_pk_bf16_f32 v39, v40, v41
	v_cvt_pk_bf16_f32 v40, v34, v35
	v_cvt_pk_bf16_f32 v41, v36, v37
	global_store_dwordx4 v[24:25], v[38:41], off nt
	v_cvt_pk_bf16_f32 v30, v30, v31
	v_cvt_pk_bf16_f32 v31, v32, v33
	v_cvt_pk_bf16_f32 v32, v26, v27
	v_cvt_pk_bf16_f32 v33, v28, v29
	global_store_dwordx4 v[238:239], v[30:33], off nt
	s_andn2_b64 vcc, exec, s[52:53]
	s_mov_b64 s[0:1], -1
	s_cbranch_vccnz .LBB0_325
